# v27 + gate|up tile preheader no longer waits vmcnt(0) for the previous tile's stores (wait moved to the execz skip path of the last epilogue pass)
# speedup vs baseline: 1.0023x; 1.0023x over previous
; #define PG8_BAR __builtin_amdgcn_s_barrier()
; template <class Epi, class Sched, bool ALIGN_EPI = false, bool SP2 = false>
; __device__ __forceinline__ void gemm_phase(PG8_LAS unsigned char* lds, const Gemm g, const Sched& S, const Epi& E) {
;     ...
;         const bool has_next = S.next(ui + 1, nxt);
;         const char* nA = has_next ? (const char*)g.A + PG8_AROW(nxt.pm) + (size_t)nxt.ks * K * 2 : cA; const char* nB = has_next ? (const char*)g.Bt + (size_t)nxt.pn * tstep + (size_t)nxt.ks * K * 2 : cB;
;     ...
;         if (!has_next) break;
; #pragma unroll
;         for (int a = 0; a < 2; ++a)
; #pragma unroll
;             for (int b = 0; b < 2; ++b)
; #pragma unroll
;                 for (int m = 0; m < 4; ++m)
; #pragma unroll
;                     for (int n = 0; n < 2; ++n) acc[a][b][m][n] = (f32x4){0.f, 0.f, 0.f, 0.f};
;         cur = nxt; cA = nA; cB = nB; ++ui;
;         if constexpr (ALIGN_EPI) { if (wr == 1) PG8_BAR; }
.LBB0_642:
	s_ashr_i32 s19, s18, 31
	s_lshl_b64 s[22:23], s[18:19], 20
	s_add_u32 s22, s0, s22
	s_addc_u32 s23, s1, s23
	s_and_b64 s[26:27], s[44:45], exec
	s_cselect_b32 s19, s23, s49
	s_cselect_b32 s26, s22, s48
	s_add_u32 s24, s24, 0x80080
	s_addc_u32 s25, s25, 0
	s_add_u32 s27, s48, 0x100
	v_mov_b32_e32 v6, 0
	s_addc_u32 s47, s49, 0
	s_mov_b32 s51, -2
	v_mov_b32_e32 v7, v6
	v_mov_b32_e32 v8, v6
	v_mov_b32_e32 v9, v6
	v_mov_b32_e32 v2, v6
	v_mov_b32_e32 v3, v6
	v_mov_b32_e32 v4, v6
	v_mov_b32_e32 v5, v6
	v_mov_b32_e32 v22, v6
	v_mov_b32_e32 v23, v6
	v_mov_b32_e32 v24, v6
	v_mov_b32_e32 v25, v6
	v_mov_b32_e32 v18, v6
	v_mov_b32_e32 v19, v6
	v_mov_b32_e32 v20, v6
	v_mov_b32_e32 v21, v6
	v_mov_b32_e32 v38, v6
	v_mov_b32_e32 v39, v6
	v_mov_b32_e32 v40, v6
	v_mov_b32_e32 v41, v6
	v_mov_b32_e32 v34, v6
	v_mov_b32_e32 v35, v6
	v_mov_b32_e32 v36, v6
	v_mov_b32_e32 v37, v6
	v_mov_b32_e32 v54, v6
	v_mov_b32_e32 v55, v6
	v_mov_b32_e32 v56, v6
	v_mov_b32_e32 v57, v6
	v_mov_b32_e32 v50, v6
	v_mov_b32_e32 v51, v6
	v_mov_b32_e32 v52, v6
	v_mov_b32_e32 v53, v6
	v_mov_b32_e32 v10, v6
	v_mov_b32_e32 v11, v6
	v_mov_b32_e32 v12, v6
	v_mov_b32_e32 v13, v6
	v_mov_b32_e32 v14, v6
	v_mov_b32_e32 v15, v6
	v_mov_b32_e32 v16, v6
	v_mov_b32_e32 v17, v6
	v_mov_b32_e32 v26, v6
	v_mov_b32_e32 v27, v6
	v_mov_b32_e32 v28, v6
	v_mov_b32_e32 v29, v6
	v_mov_b32_e32 v30, v6
	v_mov_b32_e32 v31, v6
	v_mov_b32_e32 v32, v6
	v_mov_b32_e32 v33, v6
	v_mov_b32_e32 v42, v6
	v_mov_b32_e32 v43, v6
	v_mov_b32_e32 v44, v6
	v_mov_b32_e32 v45, v6
	v_mov_b32_e32 v46, v6
	v_mov_b32_e32 v47, v6
	v_mov_b32_e32 v48, v6
	v_mov_b32_e32 v49, v6
	v_mov_b32_e32 v58, v6
	v_mov_b32_e32 v59, v6
	v_mov_b32_e32 v60, v6
	v_mov_b32_e32 v61, v6
	v_mov_b32_e32 v62, v6
	v_mov_b32_e32 v63, v6
	v_mov_b32_e32 v64, v6
	v_mov_b32_e32 v65, v6
	v_mov_b32_e32 v70, v6
	v_mov_b32_e32 v71, v6
	v_mov_b32_e32 v72, v6
	v_mov_b32_e32 v73, v6
	v_mov_b32_e32 v66, v6
	v_mov_b32_e32 v67, v6
	v_mov_b32_e32 v68, v6
	v_mov_b32_e32 v69, v6
	v_mov_b32_e32 v86, v6
	v_mov_b32_e32 v87, v6
	v_mov_b32_e32 v88, v6
	v_mov_b32_e32 v89, v6
	v_mov_b32_e32 v82, v6
	v_mov_b32_e32 v83, v6
	v_mov_b32_e32 v84, v6
	v_mov_b32_e32 v85, v6
	v_mov_b32_e32 v102, v6
	v_mov_b32_e32 v103, v6
	v_mov_b32_e32 v104, v6
	v_mov_b32_e32 v105, v6
	v_mov_b32_e32 v98, v6
	v_mov_b32_e32 v99, v6
	v_mov_b32_e32 v100, v6
	v_mov_b32_e32 v101, v6
	v_mov_b32_e32 v118, v6
	v_mov_b32_e32 v119, v6
	v_mov_b32_e32 v120, v6
	v_mov_b32_e32 v121, v6
	v_mov_b32_e32 v114, v6
	v_mov_b32_e32 v115, v6
	v_mov_b32_e32 v116, v6
	v_mov_b32_e32 v117, v6
	v_mov_b32_e32 v74, v6
	v_mov_b32_e32 v75, v6
	v_mov_b32_e32 v76, v6
	v_mov_b32_e32 v77, v6
	v_mov_b32_e32 v78, v6
	v_mov_b32_e32 v79, v6
	v_mov_b32_e32 v80, v6
	v_mov_b32_e32 v81, v6
	v_mov_b32_e32 v90, v6
	v_mov_b32_e32 v91, v6
	v_mov_b32_e32 v92, v6
	v_mov_b32_e32 v93, v6
	v_mov_b32_e32 v94, v6
	v_mov_b32_e32 v95, v6
	v_mov_b32_e32 v96, v6
	v_mov_b32_e32 v97, v6
	v_mov_b32_e32 v106, v6
	v_mov_b32_e32 v107, v6
	v_mov_b32_e32 v108, v6
	v_mov_b32_e32 v109, v6
	v_mov_b32_e32 v110, v6
	v_mov_b32_e32 v111, v6
	v_mov_b32_e32 v112, v6
	v_mov_b32_e32 v113, v6
	v_mov_b32_e32 v122, v6
	v_mov_b32_e32 v123, v6
	v_mov_b32_e32 v124, v6
	v_mov_b32_e32 v125, v6
	v_mov_b32_e32 v126, v6
	v_mov_b32_e32 v127, v6
	v_mov_b32_e32 v128, v6
	v_mov_b32_e32 v129, v6

; __device__ __forceinline__ unsigned cvt_pk_bf16(float lo, float hi) { unsigned r; asm volatile("v_cvt_pk_bf16_f32 %0, %1, %2" : "=v"(r) : "v"(lo), "v"(hi)); return r; }
;     __device__ __forceinline__ void operator()(const f32x4 (&acc)[2][2][4][2], const Unit& u, int wr, int wc, int fr_in, int fq_in, PG8_LAS unsigned char* lds, int tid_in, int quad = -1) const {
;     ...
;                 if ((u.pm == 0 ? rl < 254 : rl >= 2) && row < MT) {
;                     u32x4 w; w.x = cvt_pk_bf16(o[0], o[1]); w.y = cvt_pk_bf16(o[2], o[3]); w.z = cvt_pk_bf16(o[4], o[5]); w.w = cvt_pk_bf16(o[6], o[7]);
;                     *(u32x4*)(act + (size_t)row * DFF + col) = w;
;                 }
.LBB0_802:
	s_waitcnt vmcnt(0)
	s_or_b64 exec, exec, s[24:25]
	s_and_b64 vcc, exec, s[42:43]
	s_mov_b64 s[24:25], -1
	s_cbranch_vccnz .LBB0_633
